# type-B attention fast loop also anti-phase ping-pong (pure-MFMA segment QK(t)+PV(t-1) vs pure-VALU segment), 4 LDS stages, K fragments prefetched in the VALU segment
# baseline (speedup 1.0000x reference)
.LBB0_184:
	s_lshl_b32 s2, s64, 2
	s_add_i32 s2, s2, s33
	s_mul_i32 s40, s2, 0x108000
	s_mul_hi_i32 s41, s2, 0x108000
	s_add_u32 s12, s77, s40
	s_addc_u32 s13, s71, s41
	s_add_u32 s22, s72, s40
	v_ashrrev_i32_e32 v0, 31, v148
	s_addc_u32 s23, s66, s41
	v_lshrrev_b32_e32 v0, 29, v0
	s_add_u32 s14, s24, s40
	v_add_u32_e32 v0, v148, v0
	s_addc_u32 s15, s76, s41
	v_ashrrev_i32_e32 v26, 3, v0
	v_and_b32_e32 v0, -8, v0
	s_and_b64 s[2:3], s[88:89], exec
	v_sub_u32_e32 v27, v148, v0
	v_lshlrev_b32_e32 v0, 6, v26
	s_cselect_b32 s3, 0, 0x2000
	v_lshl_add_u32 v2, v27, 3, v0
	v_mov_b64_e32 v[4:5], s[14:15]
	v_lshlrev_b32_e32 v0, 4, v148
	s_cselect_b32 s2, 0x84, 4
	v_mad_i64_i32 v[4:5], s[14:15], v156, s54, v[4:5]
	v_and_b32_e32 v18, 0x70, v0
	v_mov_b32_e32 v19, v1
	s_lshl_b32 s38, s3, 7
	v_lshl_add_u64 v[4:5], v[4:5], 0, v[18:19]
	s_add_u32 s14, s22, s38
	v_ashrrev_i32_e32 v3, 31, v2
	v_lshrrev_b32_e32 v6, 1, v148
	v_and_b32_e32 v19, 31, v148
	s_addc_u32 s15, s23, 0
	v_lshlrev_b64 v[20:21], 1, v[2:3]
	v_and_or_b32 v0, v6, s5, v19
	v_lshl_add_u64 v[2:3], s[14:15], 0, v[20:21]
	s_lshl_b32 s96, s3, 1
	v_and_b32_e32 v22, 0xffffffe0, v156
	v_add_lshl_u32 v0, v0, s65, 7
	v_lshl_add_u64 v[4:5], v[4:5], 0, s[96:97]
	global_load_dwordx4 v[66:69], v[2:3], off
	global_load_dwordx4 v[78:81], v[4:5], off
	v_lshl_add_u64 v[2:3], s[12:13], 0, v[0:1]
	v_ashrrev_i32_e32 v23, 31, v22
	s_or_b32 s3, s38, 0x2000
	v_lshl_add_u64 v[2:3], v[22:23], 1, v[2:3]
	v_and_b32_e32 v0, 16, v6
	s_add_u32 s12, s22, s3
	v_lshl_add_u64 v[2:3], v[2:3], 0, v[0:1]
	s_addc_u32 s13, s23, 0
	global_load_dwordx4 v[70:73], v[2:3], off
	global_load_dwordx4 v[74:77], v[2:3], off offset:32
	v_lshl_add_u64 v[2:3], s[12:13], 0, v[20:21]
	global_load_dwordx4 v[86:89], v[4:5], off offset:128
	global_load_dwordx4 v[82:85], v[2:3], off
	v_mad_i64_i32 v[24:25], s[12:13], v156, s54, 0
	v_mad_u64_u32 v[122:123], s[12:13], v156, s4, v[18:19]
	s_add_u32 s12, s36, s96
	v_or_b32_e32 v24, v24, v18
	s_addc_u32 s13, s37, 0
	v_cmp_lt_i32_e32 vcc, v207, v206
	s_waitcnt vmcnt(14)
	v_lshl_add_u64 v[124:125], s[12:13], 0, v[24:25]
	s_add_u32 s12, s36, s38
	v_cndmask_b32_e32 v23, v205, v207, vcc
	v_mul_u32_u24_e32 v133, 0x90, v19
	v_mul_lo_u32 v18, v26, s4
	v_lshl_or_b32 v34, v22, 1, v0
	s_addc_u32 s13, s37, 0
	s_mov_b32 s3, 3
	v_mov_b32_e32 v2, v1
	v_mov_b32_e32 v3, v1
	v_mov_b32_e32 v4, v1
	v_mov_b32_e32 v5, v1
	v_mov_b32_e32 v6, v1
	v_mov_b32_e32 v7, v1
	v_mov_b32_e32 v8, v1
	v_mov_b32_e32 v9, v1
	v_mov_b32_e32 v10, v1
	v_mov_b32_e32 v11, v1
	v_mov_b32_e32 v12, v1
	v_mov_b32_e32 v13, v1
	v_mov_b32_e32 v14, v1
	v_mov_b32_e32 v15, v1
	v_mov_b32_e32 v16, v1
	v_mov_b32_e32 v17, v1
	v_lshlrev_b32_e32 v132, 2, v23
	v_lshl_add_u32 v123, v27, 4, v18
	v_lshl_add_u64 v[126:127], s[12:13], 0, v[20:21]
	v_mov_b32_e32 v18, v1
	v_mov_b32_e32 v19, v1
	v_mov_b32_e32 v20, v1
	v_mov_b32_e32 v21, v1
	v_mov_b32_e32 v22, v1
	v_mov_b32_e32 v23, v1
	v_mov_b32_e32 v24, v1
	v_mov_b32_e32 v25, v1
	v_mov_b32_e32 v26, v1
	v_mov_b32_e32 v27, v1
	v_mov_b32_e32 v28, v1
	v_mov_b32_e32 v29, v1
	v_mov_b32_e32 v30, v1
	v_mov_b32_e32 v31, v1
	v_mov_b32_e32 v32, v1
	v_mov_b32_e32 v33, v1
	v_mov_b32_e32 v134, 0
	v_bfrev_b32_e32 v218, 1
	v_mov_b32_e32 v219, v218
	v_mov_b32_e32 v220, v218
	v_mov_b32_e32 v221, v218
	v_mov_b32_e32 v222, v218
	v_mov_b32_e32 v223, v218
	v_mov_b32_e32 v224, v218
	v_mov_b32_e32 v225, v218
	v_mov_b32_e32 v226, v218
	v_mov_b32_e32 v227, v218
	v_mov_b32_e32 v228, v218
	v_mov_b32_e32 v229, v218
	v_mov_b32_e32 v230, v218
	v_mov_b32_e32 v231, v218
	v_mov_b32_e32 v232, v218
	v_mov_b32_e32 v233, v218
	v_add_u32_e32 v135, v133, v34
	v_mov_b32_e32 v136, 0
	s_waitcnt vmcnt(5)
	ds_write_b128 v123, v[66:69]
	s_waitcnt vmcnt(4)
	ds_write_b128 v122, v[78:81] offset:9216
	s_waitcnt lgkmcnt(0)
	s_barrier
	s_cmp_lg_u32 s98, 0
	s_cbranch_scc1 .LBB0_186_sl
	v_lshl_add_u64 v[238:239], v[126:127], 0, s[40:41]
	v_lshl_add_u64 v[242:243], v[124:125], 0, s[40:41]
	s_mov_b32 s12, 0x6e73800
	s_mov_b32 s13, 0
	v_lshl_add_u64 v[240:241], v[238:239], 0, s[12:13]
	s_mov_b32 s12, 0x6e71800
	v_lshl_add_u64 v[238:239], v[238:239], 0, s[12:13]
	s_mov_b32 s12, 0x76ad900
	v_lshl_add_u64 v[242:243], v[242:243], 0, s[12:13]
	v_readfirstlane_b32 s13, v200
	s_lshr_b32 s13, s13, 8
	v_add_u32_e32 v182, v133, v0
	v_add_u32_e32 v183, 0x9000, v182
	s_waitcnt vmcnt(0)
	ds_write_b128 v123, v[82:85] offset:18432
	ds_write_b128 v122, v[86:89] offset:27648
	global_load_dwordx4 v[66:69], v[238:239], off
	global_load_dwordx4 v[78:81], v[242:243], off
	global_load_dwordx4 v[82:85], v[240:241], off
	global_load_dwordx4 v[86:89], v[242:243], off offset:128
	v_lshl_add_u64 v[242:243], v[242:243], 0, s[30:31]
	v_lshl_add_u64 v[238:239], v[238:239], 0, s[28:29]
	v_lshl_add_u64 v[240:241], v[240:241], 0, s[28:29]
	s_waitcnt lgkmcnt(0)
	s_barrier
	s_cmp_lg_u32 s13, 0
	s_cbranch_scc0 .Lppb_nolag
	s_barrier
.Lppb_nolag:
	ds_read_b128 v[158:161], v135
	ds_read_b128 v[162:165], v135 offset:32
	ds_read_b128 v[166:169], v135 offset:4608
	ds_read_b128 v[170:173], v135 offset:4640
	s_waitcnt lgkmcnt(3)
	s_nop 0
	v_mfma_f32_32x32x16_bf16 v[50:65], v[158:161], v[70:73], v[218:233]
	s_waitcnt lgkmcnt(1)
	v_mfma_f32_32x32x16_bf16 v[34:49], v[166:169], v[70:73], v[218:233]
	v_mfma_f32_32x32x16_bf16 v[50:65], v[162:165], v[74:77], v[50:65]
	s_waitcnt lgkmcnt(0)
	v_mfma_f32_32x32x16_bf16 v[34:49], v[170:173], v[74:77], v[34:49]
	s_nop 15
	s_barrier
	v_max3_f32 v234, v50, v51, v52
	v_max3_f32 v235, v34, v35, v36
	v_max3_f32 v234, v234, v53, v54
	v_max3_f32 v234, v234, v55, v56
	v_max3_f32 v234, v234, v57, v58
	v_max3_f32 v234, v234, v59, v60
	v_max3_f32 v234, v234, v61, v62
	v_max3_f32 v234, v234, v63, v64
	v_max3_f32 v235, v235, v37, v38
	v_max3_f32 v235, v235, v39, v40
	v_max3_f32 v235, v235, v41, v42
	v_max3_f32 v235, v235, v43, v44
	v_max3_f32 v235, v235, v45, v46
	v_max3_f32 v235, v235, v47, v48
	v_max3_f32 v234, v234, v65, v49
	v_max_f32_e32 v234, v234, v235
	ds_bpermute_b32 v235, v132, v234
	s_waitcnt lgkmcnt(0)
	v_max_f32_e32 v234, v234, v235
	v_add_f32_e32 v134, v134, v234
	v_xor_b32_e32 v218, 0x80000000, v234
	v_mov_b32_e32 v219, v218
	v_mov_b32_e32 v220, v218
	v_mov_b32_e32 v221, v218
	v_mov_b32_e32 v222, v218
	v_mov_b32_e32 v223, v218
	v_mov_b32_e32 v224, v218
	v_mov_b32_e32 v225, v218
	v_mov_b32_e32 v226, v218
	v_mov_b32_e32 v227, v218
	v_mov_b32_e32 v228, v218
	v_mov_b32_e32 v229, v218
	v_mov_b32_e32 v230, v218
	v_mov_b32_e32 v231, v218
	v_mov_b32_e32 v232, v218
	v_mov_b32_e32 v233, v218
	v_sub_f32_e32 v50, v50, v234
	v_sub_f32_e32 v51, v51, v234
	v_sub_f32_e32 v52, v52, v234
	v_sub_f32_e32 v53, v53, v234
	v_sub_f32_e32 v54, v54, v234
	v_sub_f32_e32 v55, v55, v234
	v_sub_f32_e32 v56, v56, v234
	v_sub_f32_e32 v57, v57, v234
	v_sub_f32_e32 v58, v58, v234
	v_sub_f32_e32 v59, v59, v234
	v_sub_f32_e32 v60, v60, v234
	v_sub_f32_e32 v61, v61, v234
	v_sub_f32_e32 v62, v62, v234
	v_sub_f32_e32 v63, v63, v234
	v_sub_f32_e32 v64, v64, v234
	v_sub_f32_e32 v65, v65, v234
	v_sub_f32_e32 v34, v34, v234
	v_sub_f32_e32 v35, v35, v234
	v_sub_f32_e32 v36, v36, v234
	v_sub_f32_e32 v37, v37, v234
	v_sub_f32_e32 v38, v38, v234
	v_sub_f32_e32 v39, v39, v234
	v_sub_f32_e32 v40, v40, v234
	v_sub_f32_e32 v41, v41, v234
	v_sub_f32_e32 v42, v42, v234
	v_sub_f32_e32 v43, v43, v234
	v_sub_f32_e32 v44, v44, v234
	v_sub_f32_e32 v45, v45, v234
	v_sub_f32_e32 v46, v46, v234
	v_sub_f32_e32 v47, v47, v234
	v_sub_f32_e32 v48, v48, v234
	v_sub_f32_e32 v49, v49, v234
	v_exp_f32_e32 v50, v50
	v_exp_f32_e32 v51, v51
	v_exp_f32_e32 v52, v52
	v_exp_f32_e32 v53, v53
	v_exp_f32_e32 v54, v54
	v_exp_f32_e32 v55, v55
	v_exp_f32_e32 v56, v56
	v_exp_f32_e32 v57, v57
	v_cvt_pk_bf16_f32 v138, v50, v51
	v_cvt_pk_bf16_f32 v139, v52, v53
	v_cvt_pk_bf16_f32 v140, v54, v55
	v_cvt_pk_bf16_f32 v141, v56, v57
	v_exp_f32_e32 v58, v58
	v_exp_f32_e32 v59, v59
	v_exp_f32_e32 v60, v60
	v_exp_f32_e32 v61, v61
	v_exp_f32_e32 v62, v62
	v_exp_f32_e32 v63, v63
	v_exp_f32_e32 v64, v64
	v_exp_f32_e32 v65, v65
	v_cvt_pk_bf16_f32 v142, v58, v59
	v_cvt_pk_bf16_f32 v143, v60, v61
	v_cvt_pk_bf16_f32 v144, v62, v63
	v_cvt_pk_bf16_f32 v145, v64, v65
	s_waitcnt vmcnt(2)
	ds_write_b128 v123, v[66:69] offset:36864
	ds_write_b128 v122, v[78:81] offset:46080
	global_load_dwordx4 v[66:69], v[238:239], off
	global_load_dwordx4 v[78:81], v[242:243], off
	v_exp_f32_e32 v34, v34
	v_exp_f32_e32 v35, v35
	v_exp_f32_e32 v36, v36
	v_exp_f32_e32 v37, v37
	v_exp_f32_e32 v38, v38
	v_exp_f32_e32 v39, v39
	v_exp_f32_e32 v40, v40
	v_exp_f32_e32 v41, v41
	v_cvt_pk_bf16_f32 v174, v34, v35
	v_cvt_pk_bf16_f32 v175, v36, v37
	v_cvt_pk_bf16_f32 v176, v38, v39
	v_cvt_pk_bf16_f32 v177, v40, v41
	v_exp_f32_e32 v42, v42
	v_exp_f32_e32 v43, v43
	v_exp_f32_e32 v44, v44
	v_exp_f32_e32 v45, v45
	v_exp_f32_e32 v46, v46
	v_exp_f32_e32 v47, v47
	v_exp_f32_e32 v48, v48
	v_exp_f32_e32 v49, v49
	v_cvt_pk_bf16_f32 v178, v42, v43
	v_cvt_pk_bf16_f32 v179, v44, v45
	v_cvt_pk_bf16_f32 v180, v46, v47
	v_cvt_pk_bf16_f32 v181, v48, v49
	ds_read_b128 v[158:161], v135 offset:18432
	ds_read_b128 v[162:165], v135 offset:18464
	ds_read_b128 v[166:169], v135 offset:23040
	ds_read_b128 v[170:173], v135 offset:23072
	v_add_f32_e32 v234, v50, v51
	v_add_f32_e32 v235, v34, v35
	v_add_f32_e32 v234, v52, v234
	v_add_f32_e32 v235, v36, v235
	v_add_f32_e32 v234, v53, v234
	v_add_f32_e32 v235, v37, v235
	v_add_f32_e32 v234, v54, v234
	v_add_f32_e32 v235, v38, v235
	v_add_f32_e32 v234, v55, v234
	v_add_f32_e32 v235, v39, v235
	v_add_f32_e32 v234, v56, v234
	v_add_f32_e32 v235, v40, v235
	v_add_f32_e32 v234, v57, v234
	v_add_f32_e32 v235, v41, v235
	v_add_f32_e32 v234, v58, v234
	v_add_f32_e32 v235, v42, v235
	v_add_f32_e32 v234, v59, v234
	v_add_f32_e32 v235, v43, v235
	v_add_f32_e32 v234, v60, v234
	v_add_f32_e32 v235, v44, v235
	v_add_f32_e32 v234, v61, v234
	v_add_f32_e32 v235, v45, v235
	v_add_f32_e32 v234, v62, v234
	v_add_f32_e32 v235, v46, v235
	v_add_f32_e32 v234, v63, v234
	v_add_f32_e32 v235, v47, v235
	v_add_f32_e32 v234, v64, v234
	v_add_f32_e32 v235, v48, v235
	v_add_f32_e32 v234, v65, v234
	v_add_f32_e32 v235, v49, v235
	v_add_f32_e32 v234, v235, v234
	v_add_f32_e32 v136, v136, v234
	s_waitcnt lgkmcnt(0)
	s_barrier
	s_mov_b32 s3, 0
.Lppb_loop:
	ds_read_b128 v[118:121], v182 offset:9216
	ds_read_b128 v[102:105], v182 offset:13824
	ds_read_b128 v[114:117], v182 offset:9248
	ds_read_b128 v[98:101], v182 offset:13856
	ds_read_b128 v[110:113], v182 offset:9280
	ds_read_b128 v[90:93], v182 offset:13888
	ds_read_b128 v[106:109], v182 offset:9312
	ds_read_b128 v[94:97], v182 offset:13920
	v_mfma_f32_32x32x16_bf16 v[50:65], v[158:161], v[70:73], v[218:233]
	v_mfma_f32_32x32x16_bf16 v[34:49], v[166:169], v[70:73], v[218:233]
	v_mfma_f32_32x32x16_bf16 v[50:65], v[162:165], v[74:77], v[50:65]
	v_mfma_f32_32x32x16_bf16 v[34:49], v[170:173], v[74:77], v[34:49]
	s_waitcnt lgkmcnt(7)
	v_mfma_f32_32x32x16_bf16 v[2:17], v[118:121], v[138:141], v[2:17]
	s_waitcnt lgkmcnt(6)
	v_mfma_f32_32x32x16_bf16 v[18:33], v[102:105], v[138:141], v[18:33]
	s_waitcnt lgkmcnt(5)
	v_mfma_f32_32x32x16_bf16 v[2:17], v[114:117], v[142:145], v[2:17]
	s_waitcnt lgkmcnt(4)
	v_mfma_f32_32x32x16_bf16 v[18:33], v[98:101], v[142:145], v[18:33]
	s_waitcnt lgkmcnt(3)
	v_mfma_f32_32x32x16_bf16 v[2:17], v[110:113], v[174:177], v[2:17]
	s_waitcnt lgkmcnt(2)
	v_mfma_f32_32x32x16_bf16 v[18:33], v[90:93], v[174:177], v[18:33]
	s_waitcnt lgkmcnt(1)
	v_mfma_f32_32x32x16_bf16 v[2:17], v[106:109], v[178:181], v[2:17]
	s_waitcnt lgkmcnt(0)
	v_mfma_f32_32x32x16_bf16 v[18:33], v[94:97], v[178:181], v[18:33]
	s_barrier
	v_exp_f32_e32 v50, v50
	v_exp_f32_e32 v51, v51
	v_exp_f32_e32 v52, v52
	v_exp_f32_e32 v53, v53
	v_exp_f32_e32 v54, v54
	v_exp_f32_e32 v55, v55
	v_exp_f32_e32 v56, v56
	v_exp_f32_e32 v57, v57
	v_cvt_pk_bf16_f32 v138, v50, v51
	v_cvt_pk_bf16_f32 v139, v52, v53
	v_cvt_pk_bf16_f32 v140, v54, v55
	v_cvt_pk_bf16_f32 v141, v56, v57
	v_exp_f32_e32 v58, v58
	v_exp_f32_e32 v59, v59
	v_exp_f32_e32 v60, v60
	v_exp_f32_e32 v61, v61
	v_exp_f32_e32 v62, v62
	v_exp_f32_e32 v63, v63
	v_exp_f32_e32 v64, v64
	v_exp_f32_e32 v65, v65
	v_cvt_pk_bf16_f32 v142, v58, v59
	v_cvt_pk_bf16_f32 v143, v60, v61
	v_cvt_pk_bf16_f32 v144, v62, v63
	v_cvt_pk_bf16_f32 v145, v64, v65
	s_waitcnt vmcnt(2)
	ds_write_b128 v123, v[82:85] offset:55296
	ds_write_b128 v122, v[86:89] offset:64512
	global_load_dwordx4 v[82:85], v[240:241], off
	global_load_dwordx4 v[86:89], v[242:243], off offset:128
	v_exp_f32_e32 v34, v34
	v_exp_f32_e32 v35, v35
	v_exp_f32_e32 v36, v36
	v_exp_f32_e32 v37, v37
	v_exp_f32_e32 v38, v38
	v_exp_f32_e32 v39, v39
	v_exp_f32_e32 v40, v40
	v_exp_f32_e32 v41, v41
	v_cvt_pk_bf16_f32 v174, v34, v35
	v_cvt_pk_bf16_f32 v175, v36, v37
	v_cvt_pk_bf16_f32 v176, v38, v39
	v_cvt_pk_bf16_f32 v177, v40, v41
	v_exp_f32_e32 v42, v42
	v_exp_f32_e32 v43, v43
	v_exp_f32_e32 v44, v44
	v_exp_f32_e32 v45, v45
	v_exp_f32_e32 v46, v46
	v_exp_f32_e32 v47, v47
	v_exp_f32_e32 v48, v48
	v_exp_f32_e32 v49, v49
	v_cvt_pk_bf16_f32 v178, v42, v43
	v_cvt_pk_bf16_f32 v179, v44, v45
	v_cvt_pk_bf16_f32 v180, v46, v47
	v_cvt_pk_bf16_f32 v181, v48, v49
	ds_read_b128 v[158:161], v135 offset:36864
	ds_read_b128 v[162:165], v135 offset:36896
	ds_read_b128 v[166:169], v135 offset:41472
	ds_read_b128 v[170:173], v135 offset:41504
	v_add_f32_e32 v234, v50, v51
	v_add_f32_e32 v235, v34, v35
	v_add_f32_e32 v234, v52, v234
	v_add_f32_e32 v235, v36, v235
	v_add_f32_e32 v234, v53, v234
	v_add_f32_e32 v235, v37, v235
	v_add_f32_e32 v234, v54, v234
	v_add_f32_e32 v235, v38, v235
	v_add_f32_e32 v234, v55, v234
	v_add_f32_e32 v235, v39, v235
	v_add_f32_e32 v234, v56, v234
	v_add_f32_e32 v235, v40, v235
	v_add_f32_e32 v234, v57, v234
	v_add_f32_e32 v235, v41, v235
	v_add_f32_e32 v234, v58, v234
	v_add_f32_e32 v235, v42, v235
	v_add_f32_e32 v234, v59, v234
	v_add_f32_e32 v235, v43, v235
	v_add_f32_e32 v234, v60, v234
	v_add_f32_e32 v235, v44, v235
	v_add_f32_e32 v234, v61, v234
	v_add_f32_e32 v235, v45, v235
	v_add_f32_e32 v234, v62, v234
	v_add_f32_e32 v235, v46, v235
	v_add_f32_e32 v234, v63, v234
	v_add_f32_e32 v235, v47, v235
	v_add_f32_e32 v234, v64, v234
	v_add_f32_e32 v235, v48, v235
	v_add_f32_e32 v234, v65, v234
	v_add_f32_e32 v235, v49, v235
	v_add_f32_e32 v234, v235, v234
	v_add_f32_e32 v136, v136, v234
	v_lshl_add_u64 v[242:243], v[242:243], 0, s[30:31]
	v_lshl_add_u64 v[238:239], v[238:239], 0, s[28:29]
	v_lshl_add_u64 v[240:241], v[240:241], 0, s[28:29]
	s_waitcnt lgkmcnt(0)
	s_barrier
	ds_read_b128 v[118:121], v182 offset:27648
	ds_read_b128 v[102:105], v182 offset:32256
	ds_read_b128 v[114:117], v182 offset:27680
	ds_read_b128 v[98:101], v182 offset:32288
	ds_read_b128 v[110:113], v182 offset:27712
	ds_read_b128 v[90:93], v182 offset:32320
	ds_read_b128 v[106:109], v182 offset:27744
	ds_read_b128 v[94:97], v182 offset:32352
	v_mfma_f32_32x32x16_bf16 v[50:65], v[158:161], v[70:73], v[218:233]
	v_mfma_f32_32x32x16_bf16 v[34:49], v[166:169], v[70:73], v[218:233]
	v_mfma_f32_32x32x16_bf16 v[50:65], v[162:165], v[74:77], v[50:65]
	v_mfma_f32_32x32x16_bf16 v[34:49], v[170:173], v[74:77], v[34:49]
	s_waitcnt lgkmcnt(7)
	v_mfma_f32_32x32x16_bf16 v[2:17], v[118:121], v[138:141], v[2:17]
	s_waitcnt lgkmcnt(6)
	v_mfma_f32_32x32x16_bf16 v[18:33], v[102:105], v[138:141], v[18:33]
	s_waitcnt lgkmcnt(5)
	v_mfma_f32_32x32x16_bf16 v[2:17], v[114:117], v[142:145], v[2:17]
	s_waitcnt lgkmcnt(4)
	v_mfma_f32_32x32x16_bf16 v[18:33], v[98:101], v[142:145], v[18:33]
	s_waitcnt lgkmcnt(3)
	v_mfma_f32_32x32x16_bf16 v[2:17], v[110:113], v[174:177], v[2:17]
	s_waitcnt lgkmcnt(2)
	v_mfma_f32_32x32x16_bf16 v[18:33], v[90:93], v[174:177], v[18:33]
	s_waitcnt lgkmcnt(1)
	v_mfma_f32_32x32x16_bf16 v[2:17], v[106:109], v[178:181], v[2:17]
	s_waitcnt lgkmcnt(0)
	v_mfma_f32_32x32x16_bf16 v[18:33], v[94:97], v[178:181], v[18:33]
	s_barrier
	v_exp_f32_e32 v50, v50
	v_exp_f32_e32 v51, v51
	v_exp_f32_e32 v52, v52
	v_exp_f32_e32 v53, v53
	v_exp_f32_e32 v54, v54
	v_exp_f32_e32 v55, v55
	v_exp_f32_e32 v56, v56
	v_exp_f32_e32 v57, v57
	v_cvt_pk_bf16_f32 v138, v50, v51
	v_cvt_pk_bf16_f32 v139, v52, v53
	v_cvt_pk_bf16_f32 v140, v54, v55
	v_cvt_pk_bf16_f32 v141, v56, v57
	v_exp_f32_e32 v58, v58
	v_exp_f32_e32 v59, v59
	v_exp_f32_e32 v60, v60
	v_exp_f32_e32 v61, v61
	v_exp_f32_e32 v62, v62
	v_exp_f32_e32 v63, v63
	v_exp_f32_e32 v64, v64
	v_exp_f32_e32 v65, v65
	v_cvt_pk_bf16_f32 v142, v58, v59
	v_cvt_pk_bf16_f32 v143, v60, v61
	v_cvt_pk_bf16_f32 v144, v62, v63
	v_cvt_pk_bf16_f32 v145, v64, v65
	s_waitcnt vmcnt(2)
	ds_write_b128 v123, v[66:69]
	ds_write_b128 v122, v[78:81] offset:9216
	global_load_dwordx4 v[66:69], v[238:239], off
	global_load_dwordx4 v[78:81], v[242:243], off
	v_exp_f32_e32 v34, v34
	v_exp_f32_e32 v35, v35
	v_exp_f32_e32 v36, v36
	v_exp_f32_e32 v37, v37
	v_exp_f32_e32 v38, v38
	v_exp_f32_e32 v39, v39
	v_exp_f32_e32 v40, v40
	v_exp_f32_e32 v41, v41
	v_cvt_pk_bf16_f32 v174, v34, v35
	v_cvt_pk_bf16_f32 v175, v36, v37
	v_cvt_pk_bf16_f32 v176, v38, v39
	v_cvt_pk_bf16_f32 v177, v40, v41
	v_exp_f32_e32 v42, v42
	v_exp_f32_e32 v43, v43
	v_exp_f32_e32 v44, v44
	v_exp_f32_e32 v45, v45
	v_exp_f32_e32 v46, v46
	v_exp_f32_e32 v47, v47
	v_exp_f32_e32 v48, v48
	v_exp_f32_e32 v49, v49
	v_cvt_pk_bf16_f32 v178, v42, v43
	v_cvt_pk_bf16_f32 v179, v44, v45
	v_cvt_pk_bf16_f32 v180, v46, v47
	v_cvt_pk_bf16_f32 v181, v48, v49
	ds_read_b128 v[158:161], v135 offset:55296
	ds_read_b128 v[162:165], v135 offset:55328
	ds_read_b128 v[166:169], v135 offset:59904
	ds_read_b128 v[170:173], v135 offset:59936
	v_add_f32_e32 v234, v50, v51
	v_add_f32_e32 v235, v34, v35
	v_add_f32_e32 v234, v52, v234
	v_add_f32_e32 v235, v36, v235
	v_add_f32_e32 v234, v53, v234
	v_add_f32_e32 v235, v37, v235
	v_add_f32_e32 v234, v54, v234
	v_add_f32_e32 v235, v38, v235
	v_add_f32_e32 v234, v55, v234
	v_add_f32_e32 v235, v39, v235
	v_add_f32_e32 v234, v56, v234
	v_add_f32_e32 v235, v40, v235
	v_add_f32_e32 v234, v57, v234
	v_add_f32_e32 v235, v41, v235
	v_add_f32_e32 v234, v58, v234
	v_add_f32_e32 v235, v42, v235
	v_add_f32_e32 v234, v59, v234
	v_add_f32_e32 v235, v43, v235
	v_add_f32_e32 v234, v60, v234
	v_add_f32_e32 v235, v44, v235
	v_add_f32_e32 v234, v61, v234
	v_add_f32_e32 v235, v45, v235
	v_add_f32_e32 v234, v62, v234
	v_add_f32_e32 v235, v46, v235
	v_add_f32_e32 v234, v63, v234
	v_add_f32_e32 v235, v47, v235
	v_add_f32_e32 v234, v64, v234
	v_add_f32_e32 v235, v48, v235
	v_add_f32_e32 v234, v65, v234
	v_add_f32_e32 v235, v49, v235
	v_add_f32_e32 v234, v235, v234
	v_add_f32_e32 v136, v136, v234
	s_waitcnt lgkmcnt(0)
	s_barrier
	ds_read_b128 v[118:121], v182 offset:46080
	ds_read_b128 v[102:105], v182 offset:50688
	ds_read_b128 v[114:117], v182 offset:46112
	ds_read_b128 v[98:101], v182 offset:50720
	ds_read_b128 v[110:113], v182 offset:46144
	ds_read_b128 v[90:93], v182 offset:50752
	ds_read_b128 v[106:109], v182 offset:46176
	ds_read_b128 v[94:97], v182 offset:50784
	v_mfma_f32_32x32x16_bf16 v[50:65], v[158:161], v[70:73], v[218:233]
	v_mfma_f32_32x32x16_bf16 v[34:49], v[166:169], v[70:73], v[218:233]
	v_mfma_f32_32x32x16_bf16 v[50:65], v[162:165], v[74:77], v[50:65]
	v_mfma_f32_32x32x16_bf16 v[34:49], v[170:173], v[74:77], v[34:49]
	s_waitcnt lgkmcnt(7)
	v_mfma_f32_32x32x16_bf16 v[2:17], v[118:121], v[138:141], v[2:17]
	s_waitcnt lgkmcnt(6)
	v_mfma_f32_32x32x16_bf16 v[18:33], v[102:105], v[138:141], v[18:33]
	s_waitcnt lgkmcnt(5)
	v_mfma_f32_32x32x16_bf16 v[2:17], v[114:117], v[142:145], v[2:17]
	s_waitcnt lgkmcnt(4)
	v_mfma_f32_32x32x16_bf16 v[18:33], v[98:101], v[142:145], v[18:33]
	s_waitcnt lgkmcnt(3)
	v_mfma_f32_32x32x16_bf16 v[2:17], v[110:113], v[174:177], v[2:17]
	s_waitcnt lgkmcnt(2)
	v_mfma_f32_32x32x16_bf16 v[18:33], v[90:93], v[174:177], v[18:33]
	s_waitcnt lgkmcnt(1)
	v_mfma_f32_32x32x16_bf16 v[2:17], v[106:109], v[178:181], v[2:17]
	s_waitcnt lgkmcnt(0)
	v_mfma_f32_32x32x16_bf16 v[18:33], v[94:97], v[178:181], v[18:33]
	s_barrier
	v_exp_f32_e32 v50, v50
	v_exp_f32_e32 v51, v51
	v_exp_f32_e32 v52, v52
	v_exp_f32_e32 v53, v53
	v_exp_f32_e32 v54, v54
	v_exp_f32_e32 v55, v55
	v_exp_f32_e32 v56, v56
	v_exp_f32_e32 v57, v57
	v_cvt_pk_bf16_f32 v138, v50, v51
	v_cvt_pk_bf16_f32 v139, v52, v53
	v_cvt_pk_bf16_f32 v140, v54, v55
	v_cvt_pk_bf16_f32 v141, v56, v57
	v_exp_f32_e32 v58, v58
	v_exp_f32_e32 v59, v59
	v_exp_f32_e32 v60, v60
	v_exp_f32_e32 v61, v61
	v_exp_f32_e32 v62, v62
	v_exp_f32_e32 v63, v63
	v_exp_f32_e32 v64, v64
	v_exp_f32_e32 v65, v65
	v_cvt_pk_bf16_f32 v142, v58, v59
	v_cvt_pk_bf16_f32 v143, v60, v61
	v_cvt_pk_bf16_f32 v144, v62, v63
	v_cvt_pk_bf16_f32 v145, v64, v65
	s_waitcnt vmcnt(2)
	ds_write_b128 v123, v[82:85] offset:18432
	ds_write_b128 v122, v[86:89] offset:27648
	global_load_dwordx4 v[82:85], v[240:241], off
	global_load_dwordx4 v[86:89], v[242:243], off offset:128
	v_exp_f32_e32 v34, v34
	v_exp_f32_e32 v35, v35
	v_exp_f32_e32 v36, v36
	v_exp_f32_e32 v37, v37
	v_exp_f32_e32 v38, v38
	v_exp_f32_e32 v39, v39
	v_exp_f32_e32 v40, v40
	v_exp_f32_e32 v41, v41
	v_cvt_pk_bf16_f32 v174, v34, v35
	v_cvt_pk_bf16_f32 v175, v36, v37
	v_cvt_pk_bf16_f32 v176, v38, v39
	v_cvt_pk_bf16_f32 v177, v40, v41
	v_exp_f32_e32 v42, v42
	v_exp_f32_e32 v43, v43
	v_exp_f32_e32 v44, v44
	v_exp_f32_e32 v45, v45
	v_exp_f32_e32 v46, v46
	v_exp_f32_e32 v47, v47
	v_exp_f32_e32 v48, v48
	v_exp_f32_e32 v49, v49
	v_cvt_pk_bf16_f32 v178, v42, v43
	v_cvt_pk_bf16_f32 v179, v44, v45
	v_cvt_pk_bf16_f32 v180, v46, v47
	v_cvt_pk_bf16_f32 v181, v48, v49
	ds_read_b128 v[158:161], v135
	ds_read_b128 v[162:165], v135 offset:32
	ds_read_b128 v[166:169], v135 offset:4608
	ds_read_b128 v[170:173], v135 offset:4640
	v_add_f32_e32 v234, v50, v51
	v_add_f32_e32 v235, v34, v35
	v_add_f32_e32 v234, v52, v234
	v_add_f32_e32 v235, v36, v235
	v_add_f32_e32 v234, v53, v234
	v_add_f32_e32 v235, v37, v235
	v_add_f32_e32 v234, v54, v234
	v_add_f32_e32 v235, v38, v235
	v_add_f32_e32 v234, v55, v234
	v_add_f32_e32 v235, v39, v235
	v_add_f32_e32 v234, v56, v234
	v_add_f32_e32 v235, v40, v235
	v_add_f32_e32 v234, v57, v234
	v_add_f32_e32 v235, v41, v235
	v_add_f32_e32 v234, v58, v234
	v_add_f32_e32 v235, v42, v235
	v_add_f32_e32 v234, v59, v234
	v_add_f32_e32 v235, v43, v235
	v_add_f32_e32 v234, v60, v234
	v_add_f32_e32 v235, v44, v235
	v_add_f32_e32 v234, v61, v234
	v_add_f32_e32 v235, v45, v235
	v_add_f32_e32 v234, v62, v234
	v_add_f32_e32 v235, v46, v235
	v_add_f32_e32 v234, v63, v234
	v_add_f32_e32 v235, v47, v235
	v_add_f32_e32 v234, v64, v234
	v_add_f32_e32 v235, v48, v235
	v_add_f32_e32 v234, v65, v234
	v_add_f32_e32 v235, v49, v235
	v_add_f32_e32 v234, v235, v234
	v_add_f32_e32 v136, v136, v234
	v_lshl_add_u64 v[242:243], v[242:243], 0, s[30:31]
	v_lshl_add_u64 v[238:239], v[238:239], 0, s[28:29]
	v_lshl_add_u64 v[240:241], v[240:241], 0, s[28:29]
	s_waitcnt lgkmcnt(0)
	s_barrier
	s_add_i32 s3, s3, 4
	s_cmp_ge_u32 s3, s2
	s_cbranch_scc1 .Lppb_fin
	ds_read_b128 v[118:121], v183 offset:27648
	ds_read_b128 v[102:105], v183 offset:32256
	ds_read_b128 v[114:117], v183 offset:27680
	ds_read_b128 v[98:101], v183 offset:32288
	ds_read_b128 v[110:113], v183 offset:27712
	ds_read_b128 v[90:93], v183 offset:32320
	ds_read_b128 v[106:109], v183 offset:27744
	ds_read_b128 v[94:97], v183 offset:32352
	v_mfma_f32_32x32x16_bf16 v[50:65], v[158:161], v[70:73], v[218:233]
	v_mfma_f32_32x32x16_bf16 v[34:49], v[166:169], v[70:73], v[218:233]
	v_mfma_f32_32x32x16_bf16 v[50:65], v[162:165], v[74:77], v[50:65]
	v_mfma_f32_32x32x16_bf16 v[34:49], v[170:173], v[74:77], v[34:49]
	s_waitcnt lgkmcnt(7)
	v_mfma_f32_32x32x16_bf16 v[2:17], v[118:121], v[138:141], v[2:17]
	s_waitcnt lgkmcnt(6)
	v_mfma_f32_32x32x16_bf16 v[18:33], v[102:105], v[138:141], v[18:33]
	s_waitcnt lgkmcnt(5)
	v_mfma_f32_32x32x16_bf16 v[2:17], v[114:117], v[142:145], v[2:17]
	s_waitcnt lgkmcnt(4)
	v_mfma_f32_32x32x16_bf16 v[18:33], v[98:101], v[142:145], v[18:33]
	s_waitcnt lgkmcnt(3)
	v_mfma_f32_32x32x16_bf16 v[2:17], v[110:113], v[174:177], v[2:17]
	s_waitcnt lgkmcnt(2)
	v_mfma_f32_32x32x16_bf16 v[18:33], v[90:93], v[174:177], v[18:33]
	s_waitcnt lgkmcnt(1)
	v_mfma_f32_32x32x16_bf16 v[2:17], v[106:109], v[178:181], v[2:17]
	s_waitcnt lgkmcnt(0)
	v_mfma_f32_32x32x16_bf16 v[18:33], v[94:97], v[178:181], v[18:33]
	s_barrier
	v_exp_f32_e32 v50, v50
	v_exp_f32_e32 v51, v51
	v_exp_f32_e32 v52, v52
	v_exp_f32_e32 v53, v53
	v_exp_f32_e32 v54, v54
	v_exp_f32_e32 v55, v55
	v_exp_f32_e32 v56, v56
	v_exp_f32_e32 v57, v57
	v_cvt_pk_bf16_f32 v138, v50, v51
	v_cvt_pk_bf16_f32 v139, v52, v53
	v_cvt_pk_bf16_f32 v140, v54, v55
	v_cvt_pk_bf16_f32 v141, v56, v57
	v_exp_f32_e32 v58, v58
	v_exp_f32_e32 v59, v59
	v_exp_f32_e32 v60, v60
	v_exp_f32_e32 v61, v61
	v_exp_f32_e32 v62, v62
	v_exp_f32_e32 v63, v63
	v_exp_f32_e32 v64, v64
	v_exp_f32_e32 v65, v65
	v_cvt_pk_bf16_f32 v142, v58, v59
	v_cvt_pk_bf16_f32 v143, v60, v61
	v_cvt_pk_bf16_f32 v144, v62, v63
	v_cvt_pk_bf16_f32 v145, v64, v65
	s_waitcnt vmcnt(2)
	ds_write_b128 v123, v[66:69] offset:36864
	ds_write_b128 v122, v[78:81] offset:46080
	global_load_dwordx4 v[66:69], v[238:239], off
	global_load_dwordx4 v[78:81], v[242:243], off
	v_exp_f32_e32 v34, v34
	v_exp_f32_e32 v35, v35
	v_exp_f32_e32 v36, v36
	v_exp_f32_e32 v37, v37
	v_exp_f32_e32 v38, v38
	v_exp_f32_e32 v39, v39
	v_exp_f32_e32 v40, v40
	v_exp_f32_e32 v41, v41
	v_cvt_pk_bf16_f32 v174, v34, v35
	v_cvt_pk_bf16_f32 v175, v36, v37
	v_cvt_pk_bf16_f32 v176, v38, v39
	v_cvt_pk_bf16_f32 v177, v40, v41
	v_exp_f32_e32 v42, v42
	v_exp_f32_e32 v43, v43
	v_exp_f32_e32 v44, v44
	v_exp_f32_e32 v45, v45
	v_exp_f32_e32 v46, v46
	v_exp_f32_e32 v47, v47
	v_exp_f32_e32 v48, v48
	v_exp_f32_e32 v49, v49
	v_cvt_pk_bf16_f32 v178, v42, v43
	v_cvt_pk_bf16_f32 v179, v44, v45
	v_cvt_pk_bf16_f32 v180, v46, v47
	v_cvt_pk_bf16_f32 v181, v48, v49
	ds_read_b128 v[158:161], v135 offset:18432
	ds_read_b128 v[162:165], v135 offset:18464
	ds_read_b128 v[166:169], v135 offset:23040
	ds_read_b128 v[170:173], v135 offset:23072
	v_add_f32_e32 v234, v50, v51
	v_add_f32_e32 v235, v34, v35
	v_add_f32_e32 v234, v52, v234
	v_add_f32_e32 v235, v36, v235
	v_add_f32_e32 v234, v53, v234
	v_add_f32_e32 v235, v37, v235
	v_add_f32_e32 v234, v54, v234
	v_add_f32_e32 v235, v38, v235
	v_add_f32_e32 v234, v55, v234
	v_add_f32_e32 v235, v39, v235
	v_add_f32_e32 v234, v56, v234
	v_add_f32_e32 v235, v40, v235
	v_add_f32_e32 v234, v57, v234
	v_add_f32_e32 v235, v41, v235
	v_add_f32_e32 v234, v58, v234
	v_add_f32_e32 v235, v42, v235
	v_add_f32_e32 v234, v59, v234
	v_add_f32_e32 v235, v43, v235
	v_add_f32_e32 v234, v60, v234
	v_add_f32_e32 v235, v44, v235
	v_add_f32_e32 v234, v61, v234
	v_add_f32_e32 v235, v45, v235
	v_add_f32_e32 v234, v62, v234
	v_add_f32_e32 v235, v46, v235
	v_add_f32_e32 v234, v63, v234
	v_add_f32_e32 v235, v47, v235
	v_add_f32_e32 v234, v64, v234
	v_add_f32_e32 v235, v48, v235
	v_add_f32_e32 v234, v65, v234
	v_add_f32_e32 v235, v49, v235
	v_add_f32_e32 v234, v235, v234
	v_add_f32_e32 v136, v136, v234
	s_waitcnt lgkmcnt(0)
	s_barrier
	s_branch .Lppb_loop
.Lppb_fin:
	ds_read_b128 v[118:121], v183 offset:27648
	ds_read_b128 v[102:105], v183 offset:32256
	ds_read_b128 v[114:117], v183 offset:27680
	ds_read_b128 v[98:101], v183 offset:32288
	ds_read_b128 v[110:113], v183 offset:27712
	ds_read_b128 v[90:93], v183 offset:32320
	ds_read_b128 v[106:109], v183 offset:27744
	ds_read_b128 v[94:97], v183 offset:32352
	s_waitcnt lgkmcnt(7)
	v_mfma_f32_32x32x16_bf16 v[2:17], v[118:121], v[138:141], v[2:17]
	s_waitcnt lgkmcnt(6)
	v_mfma_f32_32x32x16_bf16 v[18:33], v[102:105], v[138:141], v[18:33]
	s_waitcnt lgkmcnt(5)
	v_mfma_f32_32x32x16_bf16 v[2:17], v[114:117], v[142:145], v[2:17]
	s_waitcnt lgkmcnt(4)
	v_mfma_f32_32x32x16_bf16 v[18:33], v[98:101], v[142:145], v[18:33]
	s_waitcnt lgkmcnt(3)
	v_mfma_f32_32x32x16_bf16 v[2:17], v[110:113], v[174:177], v[2:17]
	s_waitcnt lgkmcnt(2)
	v_mfma_f32_32x32x16_bf16 v[18:33], v[90:93], v[174:177], v[18:33]
	s_waitcnt lgkmcnt(1)
	v_mfma_f32_32x32x16_bf16 v[2:17], v[106:109], v[178:181], v[2:17]
	s_waitcnt lgkmcnt(0)
	v_mfma_f32_32x32x16_bf16 v[18:33], v[94:97], v[178:181], v[18:33]
	s_nop 15
	s_cmp_lg_u32 s13, 0
	s_cbranch_scc1 .Lppb_nolag2
	s_barrier
.Lppb_nolag2:
	s_waitcnt vmcnt(0)
	s_branch .LBB0_196
.LBB0_185_sl:
	v_add_f32_e32 v50, 0, v50
	v_add_f32_e32 v34, 0, v34
	v_add_f32_e32 v50, v50, v51
	v_add_f32_e32 v34, v34, v35
	v_add_f32_e32 v35, v52, v50
	v_add_f32_e32 v34, v36, v34
	v_add_f32_e32 v35, v53, v35
	v_add_f32_e32 v34, v37, v34
	v_add_f32_e32 v35, v54, v35
	v_add_f32_e32 v34, v38, v34
	v_add_f32_e32 v35, v55, v35
	v_add_f32_e32 v34, v39, v34
	v_add_f32_e32 v35, v56, v35
	v_add_f32_e32 v34, v40, v34
	v_add_f32_e32 v35, v57, v35
	v_add_f32_e32 v34, v41, v34
	v_add_f32_e32 v35, v58, v35
	v_add_f32_e32 v34, v42, v34
	v_add_f32_e32 v35, v59, v35
	v_add_f32_e32 v34, v43, v34
	v_add_f32_e32 v35, v60, v35
	v_add_f32_e32 v34, v44, v34
	v_add_f32_e32 v35, v61, v35
	v_add_f32_e32 v34, v45, v34
	v_add_f32_e32 v35, v62, v35
	v_add_f32_e32 v34, v46, v34
	v_add_f32_e32 v35, v63, v35
	v_add_f32_e32 v34, v47, v34
	v_add_f32_e32 v35, v64, v35
	v_add_f32_e32 v34, v48, v34
	v_add_f32_e32 v35, v65, v35
	v_add_f32_e32 v34, v49, v34
	v_add_f32_e32 v34, v34, v35
	s_add_i32 s3, s3, 2
	v_add_f32_e32 v136, v128, v34
	v_lshl_add_u64 v[124:125], v[124:125], 0, s[30:31]
	s_cmp_lt_u32 s12, s2
	v_lshl_add_u64 v[126:127], v[126:127], 0, s[28:29]
	s_waitcnt lgkmcnt(0)
	s_barrier
	s_barrier
	s_cbranch_scc0 .LBB0_196
